# FFN-up (SwiGLU) epilogue: 8 independent silu chains in flight + scalar-base addressing
# speedup vs baseline: 1.0829x; 1.0050x over previous
; DI u16 f2bf(float x) { return (u16)(pack2(x, 0.f) & 0xffffu); }
; DI int crow(int i, int h) { return (i & 3) + 8 * (i >> 2) + 4 * h; }
; DI float sigmoidf(float x) { return __builtin_amdgcn_rcpf(1.f + __expf(-x)); }
; DI void phase_ffn_up(const Params& p, const u16* w1t, const u16* w3t, char* smem) {
;     ...
;   auto epi = [&](int xcd, int q, f32x16 (&acc)[4][2]) __attribute__((always_inline)) {
;     G256_EPI_IDS
;     const int mt = xcd * MPX + (q / (4 * (FF / 128))) * 4 + (q & 3), nt = (q >> 2) % (FF / 128);
; #pragma unroll
;     for (int ms = 0; ms < 4; ++ms)
; #pragma unroll
;       for (int i = 0; i < 16; ++i) {
;         const size_t row = (size_t)mt * 256 + wm * 128 + ms * 32 + crow(i, lh);
;         const int col = nt * 128 + wn * 32 + lr;
;         const float a = acc[ms][0][i], b = acc[ms][1][i];
;         __builtin_nontemporal_store(f2bf(a * sigmoidf(a) * b), &hb[row * FF + col]);
;       }
.LBB0_870:
	s_waitcnt lgkmcnt(1)
	v_mfma_f32_32x32x16_bf16 v[114:129], v[158:161], v[150:153], v[114:129]
	s_mul_i32 s6, s21, 0xba2f
	s_lshr_b32 s6, s6, 20
	s_bfe_u32 s8, s21, 0x70003
	s_and_b32 s6, s6, 0xffc
	s_mulk_i32 s8, 0xbb
	s_add_i32 s6, s73, s6
	s_and_b32 s7, s21, 3
	v_mfma_f32_32x32x16_bf16 v[18:33], v[134:137], v[150:153], v[18:33]
	s_bfe_u32 s8, s8, 0x5000b
	s_or_b32 s6, s6, s7
	s_lshr_b32 s7, s21, 2
	s_mul_i32 s8, s8, 22
	s_waitcnt lgkmcnt(0)
	s_barrier
	v_mfma_f32_32x32x16_bf16 v[2:17], v[134:137], v[154:157], v[2:17]
	s_sub_i32 s7, s7, s8
	v_mfma_f32_32x32x16_bf16 v[98:113], v[158:161], v[154:157], v[98:113]
	s_waitcnt vmcnt(1)
	s_and_b32 s7, s7, 0xff
	s_lshl_b32 s62, s6, 8
	s_lshl_b32 s6, s7, 7
	s_movk_i32 s8, 0x1600
	v_mfma_f32_32x32x16_bf16 v[82:97], v[142:145], v[150:153], v[82:97]
	s_and_b64 vcc, exec, s[12:13]
	v_mfma_f32_32x32x16_bf16 v[66:81], v[142:145], v[154:157], v[66:81]
	v_mfma_f32_32x32x16_bf16 v[50:65], v[138:141], v[150:153], v[50:65]
	v_mfma_f32_32x32x16_bf16 v[34:49], v[138:141], v[154:157], v[34:49]
	v_lshrrev_b32_e32 v163, 1, v196
	v_and_b32_e32 v163, 0xffffff80, v163
	v_lshrrev_b32_e32 v164, 3, v196
	v_and_b32_e32 v164, 4, v164
	v_add3_u32 v163, v163, v164, s62
	v_lshrrev_b32_e32 v164, 1, v196
	v_and_b32_e32 v164, 0x60, v164
	v_and_b32_e32 v165, 31, v196
	v_or3_b32 v164, v164, s6, v165
	s_movk_i32 s100, 0xb00
	v_mad_u32_u24 v162, v163, s100, v164
	v_lshlrev_b32_e32 v162, 1, v162
	s_add_u32 s98, s0, 0xb00
	s_addc_u32 s99, s1, 0
	v_mul_f32_e32 v130, 0xbfb8aa3b, v114
	v_mul_f32_e32 v131, 0xbfb8aa3b, v115
	v_mul_f32_e32 v132, 0xbfb8aa3b, v116
	v_mul_f32_e32 v133, 0xbfb8aa3b, v117
	v_mul_f32_e32 v134, 0xbfb8aa3b, v118
	v_mul_f32_e32 v135, 0xbfb8aa3b, v119
	v_mul_f32_e32 v136, 0xbfb8aa3b, v120
	v_mul_f32_e32 v137, 0xbfb8aa3b, v121
	v_exp_f32_e32 v130, v130
	v_exp_f32_e32 v131, v131
	v_exp_f32_e32 v132, v132
	v_exp_f32_e32 v133, v133
	v_exp_f32_e32 v134, v134
	v_exp_f32_e32 v135, v135
	v_exp_f32_e32 v136, v136
	v_exp_f32_e32 v137, v137
	v_add_f32_e32 v130, 1.0, v130
	v_add_f32_e32 v131, 1.0, v131
	v_add_f32_e32 v132, 1.0, v132
	v_add_f32_e32 v133, 1.0, v133
	v_add_f32_e32 v134, 1.0, v134
	v_add_f32_e32 v135, 1.0, v135
	v_add_f32_e32 v136, 1.0, v136
	v_add_f32_e32 v137, 1.0, v137
	v_rcp_f32_e32 v130, v130
	v_rcp_f32_e32 v131, v131
	v_rcp_f32_e32 v132, v132
	v_rcp_f32_e32 v133, v133
	v_rcp_f32_e32 v134, v134
	v_rcp_f32_e32 v135, v135
	v_rcp_f32_e32 v136, v136
	v_rcp_f32_e32 v137, v137
	v_mul_f32_e32 v130, v114, v130
	v_mul_f32_e32 v131, v115, v131
	v_mul_f32_e32 v132, v116, v132
	v_mul_f32_e32 v133, v117, v133
	v_mul_f32_e32 v134, v118, v134
	v_mul_f32_e32 v135, v119, v135
	v_mul_f32_e32 v136, v120, v136
	v_mul_f32_e32 v137, v121, v137
	v_mul_f32_e32 v130, v98, v130
	v_mul_f32_e32 v131, v99, v131
	v_mul_f32_e32 v132, v100, v132
	v_mul_f32_e32 v133, v101, v133
	v_mul_f32_e32 v134, v102, v134
	v_mul_f32_e32 v135, v103, v135
	v_mul_f32_e32 v136, v104, v136
	v_mul_f32_e32 v137, v105, v137
	v_cvt_pk_bf16_f32 v130, v130, s0
	v_cvt_pk_bf16_f32 v131, v131, s0
	v_cvt_pk_bf16_f32 v132, v132, s0
	v_cvt_pk_bf16_f32 v133, v133, s0
	v_cvt_pk_bf16_f32 v134, v134, s0
	v_cvt_pk_bf16_f32 v135, v135, s0
	v_cvt_pk_bf16_f32 v136, v136, s0
	v_cvt_pk_bf16_f32 v137, v137, s0
	global_store_short v162, v130, s[98:99] offset:-2816 nt
	global_store_short v162, v131, s[98:99] offset:2816 nt
	s_add_u32 s98, s98, 0x2c00
	s_addc_u32 s99, s99, 0
	global_store_short v162, v132, s[98:99] offset:-2816 nt
	global_store_short v162, v133, s[98:99] offset:2816 nt
	s_add_u32 s98, s98, 0x8400
	s_addc_u32 s99, s99, 0
	global_store_short v162, v134, s[98:99] offset:-2816 nt
	global_store_short v162, v135, s[98:99] offset:2816 nt
	s_add_u32 s98, s98, 0x2c00
	s_addc_u32 s99, s99, 0
	global_store_short v162, v136, s[98:99] offset:-2816 nt
	global_store_short v162, v137, s[98:99] offset:2816 nt
	s_add_u32 s98, s98, 0x8400
	s_addc_u32 s99, s99, 0
	v_mul_f32_e32 v130, 0xbfb8aa3b, v122
	v_mul_f32_e32 v131, 0xbfb8aa3b, v123
	v_mul_f32_e32 v132, 0xbfb8aa3b, v124
	v_mul_f32_e32 v133, 0xbfb8aa3b, v125
	v_mul_f32_e32 v134, 0xbfb8aa3b, v126
	v_mul_f32_e32 v135, 0xbfb8aa3b, v127
	v_mul_f32_e32 v136, 0xbfb8aa3b, v128
	v_mul_f32_e32 v137, 0xbfb8aa3b, v129
	v_exp_f32_e32 v130, v130
	v_exp_f32_e32 v131, v131
	v_exp_f32_e32 v132, v132
	v_exp_f32_e32 v133, v133
	v_exp_f32_e32 v134, v134
	v_exp_f32_e32 v135, v135
	v_exp_f32_e32 v136, v136
	v_exp_f32_e32 v137, v137
	v_add_f32_e32 v130, 1.0, v130
	v_add_f32_e32 v131, 1.0, v131
	v_add_f32_e32 v132, 1.0, v132
	v_add_f32_e32 v133, 1.0, v133
	v_add_f32_e32 v134, 1.0, v134
	v_add_f32_e32 v135, 1.0, v135
	v_add_f32_e32 v136, 1.0, v136
	v_add_f32_e32 v137, 1.0, v137
	v_rcp_f32_e32 v130, v130
	v_rcp_f32_e32 v131, v131
	v_rcp_f32_e32 v132, v132
	v_rcp_f32_e32 v133, v133
	v_rcp_f32_e32 v134, v134
	v_rcp_f32_e32 v135, v135
	v_rcp_f32_e32 v136, v136
	v_rcp_f32_e32 v137, v137
	v_mul_f32_e32 v130, v122, v130
	v_mul_f32_e32 v131, v123, v131
	v_mul_f32_e32 v132, v124, v132
	v_mul_f32_e32 v133, v125, v133
	v_mul_f32_e32 v134, v126, v134
	v_mul_f32_e32 v135, v127, v135
	v_mul_f32_e32 v136, v128, v136
	v_mul_f32_e32 v137, v129, v137
	v_mul_f32_e32 v130, v106, v130
	v_mul_f32_e32 v131, v107, v131
	v_mul_f32_e32 v132, v108, v132
	v_mul_f32_e32 v133, v109, v133
	v_mul_f32_e32 v134, v110, v134
	v_mul_f32_e32 v135, v111, v135
	v_mul_f32_e32 v136, v112, v136
	v_mul_f32_e32 v137, v113, v137
	v_cvt_pk_bf16_f32 v130, v130, s0
	v_cvt_pk_bf16_f32 v131, v131, s0
	v_cvt_pk_bf16_f32 v132, v132, s0
	v_cvt_pk_bf16_f32 v133, v133, s0
	v_cvt_pk_bf16_f32 v134, v134, s0
	v_cvt_pk_bf16_f32 v135, v135, s0
	v_cvt_pk_bf16_f32 v136, v136, s0
	v_cvt_pk_bf16_f32 v137, v137, s0
; DI u16 f2bf(float x) { return (u16)(pack2(x, 0.f) & 0xffffu); }
; DI int crow(int i, int h) { return (i & 3) + 8 * (i >> 2) + 4 * h; }
; DI float sigmoidf(float x) { return __builtin_amdgcn_rcpf(1.f + __expf(-x)); }
; DI void phase_ffn_up(const Params& p, const u16* w1t, const u16* w3t, char* smem) {
;     ...
;       for (int i = 0; i < 16; ++i) {
;         const size_t row = (size_t)mt * 256 + wm * 128 + ms * 32 + crow(i, lh);
;         const int col = nt * 128 + wn * 32 + lr;
;         const float a = acc[ms][0][i], b = acc[ms][1][i];
;         __builtin_nontemporal_store(f2bf(a * sigmoidf(a) * b), &hb[row * FF + col]);
	global_store_short v162, v130, s[98:99] offset:-2816 nt
	global_store_short v162, v131, s[98:99] offset:2816 nt
	s_add_u32 s98, s98, 0x2c00
	s_addc_u32 s99, s99, 0
	global_store_short v162, v132, s[98:99] offset:-2816 nt
	global_store_short v162, v133, s[98:99] offset:2816 nt
	s_add_u32 s98, s98, 0x8400
	s_addc_u32 s99, s99, 0
	global_store_short v162, v134, s[98:99] offset:-2816 nt
	global_store_short v162, v135, s[98:99] offset:2816 nt
	s_add_u32 s98, s98, 0x2c00
	s_addc_u32 s99, s99, 0
	global_store_short v162, v136, s[98:99] offset:-2816 nt
	global_store_short v162, v137, s[98:99] offset:2816 nt
	s_add_u32 s98, s98, 0x8400
	s_addc_u32 s99, s99, 0
	v_mul_f32_e32 v130, 0xbfb8aa3b, v82
	v_mul_f32_e32 v131, 0xbfb8aa3b, v83
	v_mul_f32_e32 v132, 0xbfb8aa3b, v84
	v_mul_f32_e32 v133, 0xbfb8aa3b, v85
	v_mul_f32_e32 v134, 0xbfb8aa3b, v86
	v_mul_f32_e32 v135, 0xbfb8aa3b, v87
	v_mul_f32_e32 v136, 0xbfb8aa3b, v88
	v_mul_f32_e32 v137, 0xbfb8aa3b, v89
	v_exp_f32_e32 v130, v130
	v_exp_f32_e32 v131, v131
	v_exp_f32_e32 v132, v132
	v_exp_f32_e32 v133, v133
	v_exp_f32_e32 v134, v134
	v_exp_f32_e32 v135, v135
	v_exp_f32_e32 v136, v136
	v_exp_f32_e32 v137, v137
	v_add_f32_e32 v130, 1.0, v130
	v_add_f32_e32 v131, 1.0, v131
	v_add_f32_e32 v132, 1.0, v132
	v_add_f32_e32 v133, 1.0, v133
	v_add_f32_e32 v134, 1.0, v134
	v_add_f32_e32 v135, 1.0, v135
	v_add_f32_e32 v136, 1.0, v136
	v_add_f32_e32 v137, 1.0, v137
	v_rcp_f32_e32 v130, v130
	v_rcp_f32_e32 v131, v131
	v_rcp_f32_e32 v132, v132
	v_rcp_f32_e32 v133, v133
	v_rcp_f32_e32 v134, v134
	v_rcp_f32_e32 v135, v135
	v_rcp_f32_e32 v136, v136
	v_rcp_f32_e32 v137, v137
	v_mul_f32_e32 v130, v82, v130
	v_mul_f32_e32 v131, v83, v131
	v_mul_f32_e32 v132, v84, v132
	v_mul_f32_e32 v133, v85, v133
	v_mul_f32_e32 v134, v86, v134
	v_mul_f32_e32 v135, v87, v135
	v_mul_f32_e32 v136, v88, v136
	v_mul_f32_e32 v137, v89, v137
	v_mul_f32_e32 v130, v66, v130
	v_mul_f32_e32 v131, v67, v131
	v_mul_f32_e32 v132, v68, v132
	v_mul_f32_e32 v133, v69, v133
	v_mul_f32_e32 v134, v70, v134
	v_mul_f32_e32 v135, v71, v135
	v_mul_f32_e32 v136, v72, v136
	v_mul_f32_e32 v137, v73, v137
	v_cvt_pk_bf16_f32 v130, v130, s0
	v_cvt_pk_bf16_f32 v131, v131, s0
	v_cvt_pk_bf16_f32 v132, v132, s0
	v_cvt_pk_bf16_f32 v133, v133, s0
	v_cvt_pk_bf16_f32 v134, v134, s0
	v_cvt_pk_bf16_f32 v135, v135, s0
	v_cvt_pk_bf16_f32 v136, v136, s0
	v_cvt_pk_bf16_f32 v137, v137, s0
	global_store_short v162, v130, s[98:99] offset:-2816 nt
	global_store_short v162, v131, s[98:99] offset:2816 nt
	s_add_u32 s98, s98, 0x2c00
	s_addc_u32 s99, s99, 0
	global_store_short v162, v132, s[98:99] offset:-2816 nt
	global_store_short v162, v133, s[98:99] offset:2816 nt
	s_add_u32 s98, s98, 0x8400
	s_addc_u32 s99, s99, 0
	global_store_short v162, v134, s[98:99] offset:-2816 nt
	global_store_short v162, v135, s[98:99] offset:2816 nt
	s_add_u32 s98, s98, 0x2c00
	s_addc_u32 s99, s99, 0
	global_store_short v162, v136, s[98:99] offset:-2816 nt
	global_store_short v162, v137, s[98:99] offset:2816 nt
	s_add_u32 s98, s98, 0x8400
	s_addc_u32 s99, s99, 0
	v_mul_f32_e32 v130, 0xbfb8aa3b, v90
	v_mul_f32_e32 v131, 0xbfb8aa3b, v91
	v_mul_f32_e32 v132, 0xbfb8aa3b, v92
	v_mul_f32_e32 v133, 0xbfb8aa3b, v93
	v_mul_f32_e32 v134, 0xbfb8aa3b, v94
	v_mul_f32_e32 v135, 0xbfb8aa3b, v95
	v_mul_f32_e32 v136, 0xbfb8aa3b, v96
	v_mul_f32_e32 v137, 0xbfb8aa3b, v97
	v_exp_f32_e32 v130, v130
	v_exp_f32_e32 v131, v131
	v_exp_f32_e32 v132, v132
	v_exp_f32_e32 v133, v133
	v_exp_f32_e32 v134, v134
	v_exp_f32_e32 v135, v135
	v_exp_f32_e32 v136, v136
	v_exp_f32_e32 v137, v137
	v_add_f32_e32 v130, 1.0, v130
	v_add_f32_e32 v131, 1.0, v131
	v_add_f32_e32 v132, 1.0, v132
	v_add_f32_e32 v133, 1.0, v133
	v_add_f32_e32 v134, 1.0, v134
	v_add_f32_e32 v135, 1.0, v135
	v_add_f32_e32 v136, 1.0, v136
	v_add_f32_e32 v137, 1.0, v137
	v_rcp_f32_e32 v130, v130
	v_rcp_f32_e32 v131, v131
	v_rcp_f32_e32 v132, v132
	v_rcp_f32_e32 v133, v133
	v_rcp_f32_e32 v134, v134
	v_rcp_f32_e32 v135, v135
	v_rcp_f32_e32 v136, v136
	v_rcp_f32_e32 v137, v137
	v_mul_f32_e32 v130, v90, v130
	v_mul_f32_e32 v131, v91, v131
	v_mul_f32_e32 v132, v92, v132
	v_mul_f32_e32 v133, v93, v133
	v_mul_f32_e32 v134, v94, v134
	v_mul_f32_e32 v135, v95, v135
	v_mul_f32_e32 v136, v96, v136
	v_mul_f32_e32 v137, v97, v137
	v_mul_f32_e32 v130, v74, v130
	v_mul_f32_e32 v131, v75, v131
	v_mul_f32_e32 v132, v76, v132
	v_mul_f32_e32 v133, v77, v133
	v_mul_f32_e32 v134, v78, v134
	v_mul_f32_e32 v135, v79, v135
	v_mul_f32_e32 v136, v80, v136
	v_mul_f32_e32 v137, v81, v137
	v_cvt_pk_bf16_f32 v130, v130, s0
	v_cvt_pk_bf16_f32 v131, v131, s0
	v_cvt_pk_bf16_f32 v132, v132, s0
	v_cvt_pk_bf16_f32 v133, v133, s0
	v_cvt_pk_bf16_f32 v134, v134, s0
	v_cvt_pk_bf16_f32 v135, v135, s0
	v_cvt_pk_bf16_f32 v136, v136, s0
	v_cvt_pk_bf16_f32 v137, v137, s0
	global_store_short v162, v130, s[98:99] offset:-2816 nt
	global_store_short v162, v131, s[98:99] offset:2816 nt
	s_add_u32 s98, s98, 0x2c00
	s_addc_u32 s99, s99, 0
	global_store_short v162, v132, s[98:99] offset:-2816 nt
	global_store_short v162, v133, s[98:99] offset:2816 nt
	s_add_u32 s98, s98, 0x8400
	s_addc_u32 s99, s99, 0
	global_store_short v162, v134, s[98:99] offset:-2816 nt
	global_store_short v162, v135, s[98:99] offset:2816 nt
	s_add_u32 s98, s98, 0x2c00
	s_addc_u32 s99, s99, 0
	global_store_short v162, v136, s[98:99] offset:-2816 nt
	global_store_short v162, v137, s[98:99] offset:2816 nt
	s_add_u32 s98, s98, 0x8400
	s_addc_u32 s99, s99, 0
	v_mul_f32_e32 v130, 0xbfb8aa3b, v50
	v_mul_f32_e32 v131, 0xbfb8aa3b, v51
	v_mul_f32_e32 v132, 0xbfb8aa3b, v52
	v_mul_f32_e32 v133, 0xbfb8aa3b, v53
	v_mul_f32_e32 v134, 0xbfb8aa3b, v54
	v_mul_f32_e32 v135, 0xbfb8aa3b, v55
; DI u16 f2bf(float x) { return (u16)(pack2(x, 0.f) & 0xffffu); }
; DI int crow(int i, int h) { return (i & 3) + 8 * (i >> 2) + 4 * h; }
; DI float sigmoidf(float x) { return __builtin_amdgcn_rcpf(1.f + __expf(-x)); }
; DI void phase_ffn_up(const Params& p, const u16* w1t, const u16* w3t, char* smem) {
;     ...
;       for (int i = 0; i < 16; ++i) {
;         const size_t row = (size_t)mt * 256 + wm * 128 + ms * 32 + crow(i, lh);
;         const int col = nt * 128 + wn * 32 + lr;
;         const float a = acc[ms][0][i], b = acc[ms][1][i];
;         __builtin_nontemporal_store(f2bf(a * sigmoidf(a) * b), &hb[row * FF + col]);
	v_mul_f32_e32 v136, 0xbfb8aa3b, v56
	v_mul_f32_e32 v137, 0xbfb8aa3b, v57
	v_exp_f32_e32 v130, v130
	v_exp_f32_e32 v131, v131
	v_exp_f32_e32 v132, v132
	v_exp_f32_e32 v133, v133
	v_exp_f32_e32 v134, v134
	v_exp_f32_e32 v135, v135
	v_exp_f32_e32 v136, v136
	v_exp_f32_e32 v137, v137
	v_add_f32_e32 v130, 1.0, v130
	v_add_f32_e32 v131, 1.0, v131
	v_add_f32_e32 v132, 1.0, v132
	v_add_f32_e32 v133, 1.0, v133
	v_add_f32_e32 v134, 1.0, v134
	v_add_f32_e32 v135, 1.0, v135
	v_add_f32_e32 v136, 1.0, v136
	v_add_f32_e32 v137, 1.0, v137
	v_rcp_f32_e32 v130, v130
	v_rcp_f32_e32 v131, v131
	v_rcp_f32_e32 v132, v132
	v_rcp_f32_e32 v133, v133
	v_rcp_f32_e32 v134, v134
	v_rcp_f32_e32 v135, v135
	v_rcp_f32_e32 v136, v136
	v_rcp_f32_e32 v137, v137
	v_mul_f32_e32 v130, v50, v130
	v_mul_f32_e32 v131, v51, v131
	v_mul_f32_e32 v132, v52, v132
	v_mul_f32_e32 v133, v53, v133
	v_mul_f32_e32 v134, v54, v134
	v_mul_f32_e32 v135, v55, v135
	v_mul_f32_e32 v136, v56, v136
	v_mul_f32_e32 v137, v57, v137
	v_mul_f32_e32 v130, v34, v130
	v_mul_f32_e32 v131, v35, v131
	v_mul_f32_e32 v132, v36, v132
	v_mul_f32_e32 v133, v37, v133
	v_mul_f32_e32 v134, v38, v134
	v_mul_f32_e32 v135, v39, v135
	v_mul_f32_e32 v136, v40, v136
	v_mul_f32_e32 v137, v41, v137
	v_cvt_pk_bf16_f32 v130, v130, s0
	v_cvt_pk_bf16_f32 v131, v131, s0
	v_cvt_pk_bf16_f32 v132, v132, s0
	v_cvt_pk_bf16_f32 v133, v133, s0
	v_cvt_pk_bf16_f32 v134, v134, s0
	v_cvt_pk_bf16_f32 v135, v135, s0
	v_cvt_pk_bf16_f32 v136, v136, s0
	v_cvt_pk_bf16_f32 v137, v137, s0
	global_store_short v162, v130, s[98:99] offset:-2816 nt
	global_store_short v162, v131, s[98:99] offset:2816 nt
	s_add_u32 s98, s98, 0x2c00
	s_addc_u32 s99, s99, 0
	global_store_short v162, v132, s[98:99] offset:-2816 nt
	global_store_short v162, v133, s[98:99] offset:2816 nt
	s_add_u32 s98, s98, 0x8400
	s_addc_u32 s99, s99, 0
	global_store_short v162, v134, s[98:99] offset:-2816 nt
	global_store_short v162, v135, s[98:99] offset:2816 nt
	s_add_u32 s98, s98, 0x2c00
	s_addc_u32 s99, s99, 0
	global_store_short v162, v136, s[98:99] offset:-2816 nt
	global_store_short v162, v137, s[98:99] offset:2816 nt
	s_add_u32 s98, s98, 0x8400
	s_addc_u32 s99, s99, 0
	v_mul_f32_e32 v130, 0xbfb8aa3b, v58
	v_mul_f32_e32 v131, 0xbfb8aa3b, v59
	v_mul_f32_e32 v132, 0xbfb8aa3b, v60
	v_mul_f32_e32 v133, 0xbfb8aa3b, v61
	v_mul_f32_e32 v134, 0xbfb8aa3b, v62
	v_mul_f32_e32 v135, 0xbfb8aa3b, v63
	v_mul_f32_e32 v136, 0xbfb8aa3b, v64
	v_mul_f32_e32 v137, 0xbfb8aa3b, v65
	v_exp_f32_e32 v130, v130
	v_exp_f32_e32 v131, v131
	v_exp_f32_e32 v132, v132
	v_exp_f32_e32 v133, v133
	v_exp_f32_e32 v134, v134
	v_exp_f32_e32 v135, v135
	v_exp_f32_e32 v136, v136
	v_exp_f32_e32 v137, v137
	v_add_f32_e32 v130, 1.0, v130
	v_add_f32_e32 v131, 1.0, v131
	v_add_f32_e32 v132, 1.0, v132
	v_add_f32_e32 v133, 1.0, v133
	v_add_f32_e32 v134, 1.0, v134
	v_add_f32_e32 v135, 1.0, v135
	v_add_f32_e32 v136, 1.0, v136
	v_add_f32_e32 v137, 1.0, v137
	v_rcp_f32_e32 v130, v130
	v_rcp_f32_e32 v131, v131
	v_rcp_f32_e32 v132, v132
	v_rcp_f32_e32 v133, v133
	v_rcp_f32_e32 v134, v134
	v_rcp_f32_e32 v135, v135
	v_rcp_f32_e32 v136, v136
	v_rcp_f32_e32 v137, v137
	v_mul_f32_e32 v130, v58, v130
	v_mul_f32_e32 v131, v59, v131
	v_mul_f32_e32 v132, v60, v132
	v_mul_f32_e32 v133, v61, v133
	v_mul_f32_e32 v134, v62, v134
	v_mul_f32_e32 v135, v63, v135
	v_mul_f32_e32 v136, v64, v136
	v_mul_f32_e32 v137, v65, v137
	v_mul_f32_e32 v130, v42, v130
	v_mul_f32_e32 v131, v43, v131
	v_mul_f32_e32 v132, v44, v132
	v_mul_f32_e32 v133, v45, v133
	v_mul_f32_e32 v134, v46, v134
	v_mul_f32_e32 v135, v47, v135
	v_mul_f32_e32 v136, v48, v136
	v_mul_f32_e32 v137, v49, v137
	v_cvt_pk_bf16_f32 v130, v130, s0
	v_cvt_pk_bf16_f32 v131, v131, s0
	v_cvt_pk_bf16_f32 v132, v132, s0
	v_cvt_pk_bf16_f32 v133, v133, s0
	v_cvt_pk_bf16_f32 v134, v134, s0
	v_cvt_pk_bf16_f32 v135, v135, s0
	v_cvt_pk_bf16_f32 v136, v136, s0
	v_cvt_pk_bf16_f32 v137, v137, s0
	global_store_short v162, v130, s[98:99] offset:-2816 nt
	global_store_short v162, v131, s[98:99] offset:2816 nt
	s_add_u32 s98, s98, 0x2c00
	s_addc_u32 s99, s99, 0
	global_store_short v162, v132, s[98:99] offset:-2816 nt
	global_store_short v162, v133, s[98:99] offset:2816 nt
	s_add_u32 s98, s98, 0x8400
	s_addc_u32 s99, s99, 0
	global_store_short v162, v134, s[98:99] offset:-2816 nt
	global_store_short v162, v135, s[98:99] offset:2816 nt
	s_add_u32 s98, s98, 0x2c00
	s_addc_u32 s99, s99, 0
	global_store_short v162, v136, s[98:99] offset:-2816 nt
	global_store_short v162, v137, s[98:99] offset:2816 nt
	s_add_u32 s98, s98, 0x8400
	s_addc_u32 s99, s99, 0
	v_mul_f32_e32 v130, 0xbfb8aa3b, v18
	v_mul_f32_e32 v131, 0xbfb8aa3b, v19
	v_mul_f32_e32 v132, 0xbfb8aa3b, v20
	v_mul_f32_e32 v133, 0xbfb8aa3b, v21
	v_mul_f32_e32 v134, 0xbfb8aa3b, v22
	v_mul_f32_e32 v135, 0xbfb8aa3b, v23
	v_mul_f32_e32 v136, 0xbfb8aa3b, v24
	v_mul_f32_e32 v137, 0xbfb8aa3b, v25
	v_exp_f32_e32 v130, v130
	v_exp_f32_e32 v131, v131
	v_exp_f32_e32 v132, v132
	v_exp_f32_e32 v133, v133
	v_exp_f32_e32 v134, v134
	v_exp_f32_e32 v135, v135
	v_exp_f32_e32 v136, v136
	v_exp_f32_e32 v137, v137
	v_add_f32_e32 v130, 1.0, v130
	v_add_f32_e32 v131, 1.0, v131
	v_add_f32_e32 v132, 1.0, v132
	v_add_f32_e32 v133, 1.0, v133
	v_add_f32_e32 v134, 1.0, v134
; DI u16 f2bf(float x) { return (u16)(pack2(x, 0.f) & 0xffffu); }
; DI int crow(int i, int h) { return (i & 3) + 8 * (i >> 2) + 4 * h; }
; DI float sigmoidf(float x) { return __builtin_amdgcn_rcpf(1.f + __expf(-x)); }
; template <class Toff, class Setup, class Epi>
; DI void gemm256_stream(int tiles_per_xcd, int K, long ais, long akcs, long bis, Toff toff, Setup setup, Epi epi, char* smem) {
;     ...
;     if (!has_next) break;
;     q = qn;
;     Ac = An;
;     Bc = Bn;
;     G256_GLOAD(Ac, Bc, 1)
; DI void phase_ffn_up(const Params& p, const u16* w1t, const u16* w3t, char* smem) {
;     ...
;       for (int i = 0; i < 16; ++i) {
;         const size_t row = (size_t)mt * 256 + wm * 128 + ms * 32 + crow(i, lh);
;         const int col = nt * 128 + wn * 32 + lr;
;         const float a = acc[ms][0][i], b = acc[ms][1][i];
;         __builtin_nontemporal_store(f2bf(a * sigmoidf(a) * b), &hb[row * FF + col]);
	v_add_f32_e32 v135, 1.0, v135
	v_add_f32_e32 v136, 1.0, v136
	v_add_f32_e32 v137, 1.0, v137
	v_rcp_f32_e32 v130, v130
	v_rcp_f32_e32 v131, v131
	v_rcp_f32_e32 v132, v132
	v_rcp_f32_e32 v133, v133
	v_rcp_f32_e32 v134, v134
	v_rcp_f32_e32 v135, v135
	v_rcp_f32_e32 v136, v136
	v_rcp_f32_e32 v137, v137
	v_mul_f32_e32 v130, v18, v130
	v_mul_f32_e32 v131, v19, v131
	v_mul_f32_e32 v132, v20, v132
	v_mul_f32_e32 v133, v21, v133
	v_mul_f32_e32 v134, v22, v134
	v_mul_f32_e32 v135, v23, v135
	v_mul_f32_e32 v136, v24, v136
	v_mul_f32_e32 v137, v25, v137
	v_mul_f32_e32 v130, v2, v130
	v_mul_f32_e32 v131, v3, v131
	v_mul_f32_e32 v132, v4, v132
	v_mul_f32_e32 v133, v5, v133
	v_mul_f32_e32 v134, v6, v134
	v_mul_f32_e32 v135, v7, v135
	v_mul_f32_e32 v136, v8, v136
	v_mul_f32_e32 v137, v9, v137
	v_cvt_pk_bf16_f32 v130, v130, s0
	v_cvt_pk_bf16_f32 v131, v131, s0
	v_cvt_pk_bf16_f32 v132, v132, s0
	v_cvt_pk_bf16_f32 v133, v133, s0
	v_cvt_pk_bf16_f32 v134, v134, s0
	v_cvt_pk_bf16_f32 v135, v135, s0
	v_cvt_pk_bf16_f32 v136, v136, s0
	v_cvt_pk_bf16_f32 v137, v137, s0
	global_store_short v162, v130, s[98:99] offset:-2816 nt
	global_store_short v162, v131, s[98:99] offset:2816 nt
	s_add_u32 s98, s98, 0x2c00
	s_addc_u32 s99, s99, 0
	global_store_short v162, v132, s[98:99] offset:-2816 nt
	global_store_short v162, v133, s[98:99] offset:2816 nt
	s_add_u32 s98, s98, 0x8400
	s_addc_u32 s99, s99, 0
	global_store_short v162, v134, s[98:99] offset:-2816 nt
	global_store_short v162, v135, s[98:99] offset:2816 nt
	s_add_u32 s98, s98, 0x2c00
	s_addc_u32 s99, s99, 0
	global_store_short v162, v136, s[98:99] offset:-2816 nt
	global_store_short v162, v137, s[98:99] offset:2816 nt
	s_add_u32 s98, s98, 0x8400
	s_addc_u32 s99, s99, 0
	v_mul_f32_e32 v130, 0xbfb8aa3b, v26
	v_mul_f32_e32 v131, 0xbfb8aa3b, v27
	v_mul_f32_e32 v132, 0xbfb8aa3b, v28
	v_mul_f32_e32 v133, 0xbfb8aa3b, v29
	v_mul_f32_e32 v134, 0xbfb8aa3b, v30
	v_mul_f32_e32 v135, 0xbfb8aa3b, v31
	v_mul_f32_e32 v136, 0xbfb8aa3b, v32
	v_mul_f32_e32 v137, 0xbfb8aa3b, v33
	v_exp_f32_e32 v130, v130
	v_exp_f32_e32 v131, v131
	v_exp_f32_e32 v132, v132
	v_exp_f32_e32 v133, v133
	v_exp_f32_e32 v134, v134
	v_exp_f32_e32 v135, v135
	v_exp_f32_e32 v136, v136
	v_exp_f32_e32 v137, v137
	v_add_f32_e32 v130, 1.0, v130
	v_add_f32_e32 v131, 1.0, v131
	v_add_f32_e32 v132, 1.0, v132
	v_add_f32_e32 v133, 1.0, v133
	v_add_f32_e32 v134, 1.0, v134
	v_add_f32_e32 v135, 1.0, v135
	v_add_f32_e32 v136, 1.0, v136
	v_add_f32_e32 v137, 1.0, v137
	v_rcp_f32_e32 v130, v130
	v_rcp_f32_e32 v131, v131
	v_rcp_f32_e32 v132, v132
	v_rcp_f32_e32 v133, v133
	v_rcp_f32_e32 v134, v134
	v_rcp_f32_e32 v135, v135
	v_rcp_f32_e32 v136, v136
	v_rcp_f32_e32 v137, v137
	v_mul_f32_e32 v130, v26, v130
	v_mul_f32_e32 v131, v27, v131
	v_mul_f32_e32 v132, v28, v132
	v_mul_f32_e32 v133, v29, v133
	v_mul_f32_e32 v134, v30, v134
	v_mul_f32_e32 v135, v31, v135
	v_mul_f32_e32 v136, v32, v136
	v_mul_f32_e32 v137, v33, v137
	v_mul_f32_e32 v130, v10, v130
	v_mul_f32_e32 v131, v11, v131
	v_mul_f32_e32 v132, v12, v132
	v_mul_f32_e32 v133, v13, v133
	v_mul_f32_e32 v134, v14, v134
	v_mul_f32_e32 v135, v15, v135
	v_mul_f32_e32 v136, v16, v136
	v_mul_f32_e32 v137, v17, v137
	v_cvt_pk_bf16_f32 v130, v130, s0
	v_cvt_pk_bf16_f32 v131, v131, s0
	v_cvt_pk_bf16_f32 v132, v132, s0
	v_cvt_pk_bf16_f32 v133, v133, s0
	v_cvt_pk_bf16_f32 v134, v134, s0
	v_cvt_pk_bf16_f32 v135, v135, s0
	v_cvt_pk_bf16_f32 v136, v136, s0
	v_cvt_pk_bf16_f32 v137, v137, s0
	global_store_short v162, v130, s[98:99] offset:-2816 nt
	global_store_short v162, v131, s[98:99] offset:2816 nt
	s_add_u32 s98, s98, 0x2c00
	s_addc_u32 s99, s99, 0
	global_store_short v162, v132, s[98:99] offset:-2816 nt
	global_store_short v162, v133, s[98:99] offset:2816 nt
	s_add_u32 s98, s98, 0x8400
	s_addc_u32 s99, s99, 0
	global_store_short v162, v134, s[98:99] offset:-2816 nt
	global_store_short v162, v135, s[98:99] offset:2816 nt
	s_add_u32 s98, s98, 0x2c00
	s_addc_u32 s99, s99, 0
	global_store_short v162, v136, s[98:99] offset:-2816 nt
	global_store_short v162, v137, s[98:99] offset:2816 nt
	s_add_u32 s98, s98, 0x8400
	s_addc_u32 s99, s99, 0
	s_mov_b64 s[8:9], -1
	s_cbranch_vccz .LBB0_849
	v_add_co_u32_e32 v2, vcc, 0x20000, v192
	global_load_dwordx4 v[142:145], v[192:193], off offset:128
	global_load_dwordx4 v[158:161], v[190:191], off offset:128
	v_addc_co_u32_e32 v3, vcc, 0, v193, vcc
	v_add_co_u32_e32 v4, vcc, 0x10000, v190
	s_mov_b64 s[8:9], 0
	s_nop 0
	v_addc_co_u32_e32 v5, vcc, 0, v191, vcc
	global_load_dwordx4 v[138:141], v[2:3], off offset:128
	global_load_dwordx4 v[154:157], v[4:5], off offset:128
	v_add_co_u32_e32 v2, vcc, 0x40000, v192
	s_nop 1
	v_addc_co_u32_e32 v3, vcc, 0, v193, vcc
	v_add_co_u32_e32 v4, vcc, 0x20000, v190
	s_nop 1
	v_addc_co_u32_e32 v5, vcc, 0, v191, vcc
	global_load_dwordx4 v[134:137], v[2:3], off offset:128
	global_load_dwordx4 v[150:153], v[4:5], off offset:128
	v_add_co_u32_e32 v2, vcc, 0x60000, v192
	s_nop 1
	v_addc_co_u32_e32 v3, vcc, 0, v193, vcc
	v_add_co_u32_e32 v4, vcc, 0x30000, v190
	s_nop 1
	v_addc_co_u32_e32 v5, vcc, 0, v191, vcc
	global_load_dwordx4 v[130:133], v[2:3], off offset:128
	global_load_dwordx4 v[146:149], v[4:5], off offset:128
	s_branch .LBB0_849
